# softmax fma/exp pairs with the temp register rotated over four registers (52 of 128 sites)
# baseline (speedup 1.0000x reference)
; #define LAS __attribute__((address_space(3)))
; __device__ __forceinline__ unsigned pk2(float lo, float hi) { return pg8::cvt_pk_bf16(lo, hi); }
; __device__ __forceinline__ float row_rs(const float* ssq, int row) { return ssq ? rsqrtf(ssq[row] * (1.f / 1024.f) + RMS_EPS) : 1.f; }
;     __device__ __forceinline__ void fused(f32x4 (&acc)[2][2][4][2], const pg8::Unit& u, int wr, int wc, int fr, int fq, LAS unsigned char* lds, int wid, int lane) const {
;         LAS bf16* QI = (LAS bf16*)lds;
; #pragma unroll
;         for (int ai = 0; ai < 2; ++ai)
; #pragma unroll
;             for (int m = 0; m < 4; ++m) { const int rl = ai * 128 + wr * 64 + m * 16 + fr; const float rs = pg8::row_rs(ssq, u.pm * 256 + rl);
; #pragma unroll
;                 for (int bj = 0; bj < 2; ++bj)
; #pragma unroll
;                     for (int n = 0; n < 2; ++n) { const f32x4 v = acc[ai][bj][m][n] * rs; v2u w; w.x = pk2(v[0], v[1]); w.y = pk2(v[2], v[3]);
;                         *(LAS v2u*)(QI + rl * XP + bj * 128 + wc * 32 + n * 16 + 4 * fq) = w; } }
.LBB0_1108:
	s_add_u32 s4, s48, 0x20000
	s_addc_u32 s5, s49, 0
	v_lshrrev_b32_e32 v128, 5, v208
	s_lshl_b32 s13, s10, 8
	v_lshlrev_b32_e32 v189, 4, v128
	v_lshlrev_b32_e32 v211, 2, v128
	v_add_u32_e32 v128, s13, v146
	v_ashrrev_i32_e32 v129, 31, v128
	v_lshl_add_u64 v[132:133], v[128:129], 2, s[4:5]
	s_barrier
	global_load_dword v131, v[132:133], off
	global_load_dword v136, v[132:133], off offset:64
	global_load_dword v137, v[132:133], off offset:128
	global_load_dword v138, v[132:133], off offset:192
	global_load_dword v139, v[132:133], off offset:512
	global_load_dword v140, v[132:133], off offset:576
	global_load_dword v141, v[132:133], off offset:640
	global_load_dword v142, v[132:133], off offset:704
	s_lshl_b32 s6, s39, 6
	v_mov_b32_e32 v129, 0x358637bd
	s_add_i32 s7, s6, 0
	s_mov_b32 s6, 0x800000
	s_movk_i32 s14, 0x210
	s_ashr_i32 s15, s10, 4
	s_add_i32 s12, 0, 0x10800
	s_andn2_b32 s30, s30, 63
	v_and_b32_e32 v210, 31, v209
	v_and_b32_e32 v188, 8, v147
	v_and_b32_e32 v190, 0x1f0, v144
	v_lshl_or_b32 v214, s31, 5, v210
	v_mov_b32_e32 v191, 0
	v_lshlrev_b32_e32 v130, 1, v188
	v_add_u32_e32 v216, 0, v190
	v_add_u32_e32 v215, s12, v190
	v_mul_u32_u24_e32 v212, 0x210, v210
	v_add3_u32 v213, 0, v212, v189
	s_mov_b32 s11, 0
	s_waitcnt vmcnt(0)
	v_fmamk_f32 v131, v131, 0x3a800000, v129
	s_nop 0
	v_rsq_f32_e32 v131, v131
	s_nop 0
	v_mov_b32_e32 v132, v131
	v_mul_lo_u32 v131, v146, s14
	v_pk_mul_f32 v[118:119], v[118:119], v[132:133] op_sel_hi:[1,0]
	v_pk_mul_f32 v[116:117], v[116:117], v[132:133] op_sel_hi:[1,0]
	v_pk_mul_f32 v[114:115], v[114:115], v[132:133] op_sel_hi:[1,0]
	v_pk_mul_f32 v[112:113], v[112:113], v[132:133] op_sel_hi:[1,0]
	v_add3_u32 v131, s7, v145, v131
	v_cvt_pk_bf16_f32 v116, v116, v117
	v_cvt_pk_bf16_f32 v117, v118, v119
	v_cvt_pk_bf16_f32 v112, v112, v113
	v_cvt_pk_bf16_f32 v113, v114, v115
	ds_write2_b64 v131, v[116:117], v[112:113] offset0:32 offset1:36
	v_pk_mul_f32 v[126:127], v[126:127], v[132:133] op_sel_hi:[1,0]
	v_pk_mul_f32 v[124:125], v[124:125], v[132:133] op_sel_hi:[1,0]
	v_pk_mul_f32 v[122:123], v[122:123], v[132:133] op_sel_hi:[1,0]
	v_pk_mul_f32 v[120:121], v[120:121], v[132:133] op_sel_hi:[1,0]
	v_cvt_pk_bf16_f32 v124, v124, v125
	v_cvt_pk_bf16_f32 v125, v126, v127
	v_cvt_pk_bf16_f32 v120, v120, v121
	v_cvt_pk_bf16_f32 v121, v122, v123
	ds_write2_b64 v131, v[124:125], v[120:121] offset1:4
	s_waitcnt vmcnt(0)
	v_fmamk_f32 v112, v136, 0x3a800000, v129
	s_nop 0
	v_rsq_f32_e32 v112, v112
	s_nop 0
	v_add_u32_e32 v113, 0x2100, v131
	v_pk_mul_f32 v[106:107], v[106:107], v[112:113] op_sel_hi:[1,0]
	v_pk_mul_f32 v[104:105], v[104:105], v[112:113] op_sel_hi:[1,0]
	v_pk_mul_f32 v[102:103], v[102:103], v[112:113] op_sel_hi:[1,0]
	v_pk_mul_f32 v[100:101], v[100:101], v[112:113] op_sel_hi:[1,0]
	v_pk_mul_f32 v[98:99], v[98:99], v[112:113] op_sel_hi:[1,0]
	v_pk_mul_f32 v[96:97], v[96:97], v[112:113] op_sel_hi:[1,0]
	v_cvt_pk_bf16_f32 v104, v104, v105
	v_cvt_pk_bf16_f32 v105, v106, v107
	v_add_u32_e32 v106, 0x2000, v131
	v_cvt_pk_bf16_f32 v100, v100, v101
	v_cvt_pk_bf16_f32 v101, v102, v103
	v_cvt_pk_bf16_f32 v96, v96, v97
	v_cvt_pk_bf16_f32 v97, v98, v99
	ds_write2_b64 v106, v[100:101], v[96:97] offset0:64 offset1:68
	v_pk_mul_f32 v[110:111], v[110:111], v[112:113] op_sel_hi:[1,0]
	v_pk_mul_f32 v[108:109], v[108:109], v[112:113] op_sel_hi:[1,0]
	s_waitcnt vmcnt(0)
	v_fmamk_f32 v96, v137, 0x3a800000, v129
	v_cvt_pk_bf16_f32 v108, v108, v109
	v_rsq_f32_e32 v96, v96
	v_cvt_pk_bf16_f32 v109, v110, v111
	ds_write2_b64 v106, v[108:109], v[104:105] offset0:32 offset1:36
	v_add_u32_e32 v97, 0x4200, v131
	v_pk_mul_f32 v[90:91], v[90:91], v[96:97] op_sel_hi:[1,0]
	v_pk_mul_f32 v[88:89], v[88:89], v[96:97] op_sel_hi:[1,0]
	v_pk_mul_f32 v[86:87], v[86:87], v[96:97] op_sel_hi:[1,0]
	v_pk_mul_f32 v[84:85], v[84:85], v[96:97] op_sel_hi:[1,0]
	v_pk_mul_f32 v[82:83], v[82:83], v[96:97] op_sel_hi:[1,0]
	v_pk_mul_f32 v[80:81], v[80:81], v[96:97] op_sel_hi:[1,0]
	v_cvt_pk_bf16_f32 v88, v88, v89
	v_cvt_pk_bf16_f32 v89, v90, v91
	v_add_u32_e32 v90, 0x4000, v131
	v_cvt_pk_bf16_f32 v84, v84, v85
	v_cvt_pk_bf16_f32 v85, v86, v87
	v_cvt_pk_bf16_f32 v80, v80, v81
	v_cvt_pk_bf16_f32 v81, v82, v83
	ds_write2_b64 v90, v[84:85], v[80:81] offset0:96 offset1:100
	v_pk_mul_f32 v[94:95], v[94:95], v[96:97] op_sel_hi:[1,0]
	v_pk_mul_f32 v[92:93], v[92:93], v[96:97] op_sel_hi:[1,0]
	s_waitcnt vmcnt(0)
	v_fmamk_f32 v80, v138, 0x3a800000, v129
	v_cvt_pk_bf16_f32 v92, v92, v93
	v_rsq_f32_e32 v80, v80
	v_cvt_pk_bf16_f32 v93, v94, v95
	ds_write2_b64 v90, v[92:93], v[88:89] offset0:64 offset1:68
	v_mov_b32_e32 v82, v80
	v_pk_mul_f32 v[74:75], v[74:75], v[82:83] op_sel_hi:[1,0]
	v_pk_mul_f32 v[72:73], v[72:73], v[82:83] op_sel_hi:[1,0]
	v_pk_mul_f32 v[70:71], v[70:71], v[82:83] op_sel_hi:[1,0]
	v_pk_mul_f32 v[68:69], v[68:69], v[82:83] op_sel_hi:[1,0]
	v_pk_mul_f32 v[66:67], v[66:67], v[82:83] op_sel_hi:[1,0]
	v_pk_mul_f32 v[64:65], v[64:65], v[82:83] op_sel_hi:[1,0]
	v_cvt_pk_bf16_f32 v72, v72, v73
	v_cvt_pk_bf16_f32 v73, v74, v75
	v_add_u32_e32 v74, 0x6000, v131
	v_cvt_pk_bf16_f32 v68, v68, v69
	v_cvt_pk_bf16_f32 v69, v70, v71
	v_cvt_pk_bf16_f32 v64, v64, v65
	v_cvt_pk_bf16_f32 v65, v66, v67
	ds_write2_b64 v74, v[68:69], v[64:65] offset0:128 offset1:132
	v_add_u32_e32 v80, 0x6300, v131
	v_pk_mul_f32 v[78:79], v[78:79], v[82:83] op_sel_hi:[1,0]
	v_pk_mul_f32 v[76:77], v[76:77], v[82:83] op_sel_hi:[1,0]
	v_add3_u32 v68, s12, v212, v189
	v_cvt_pk_bf16_f32 v76, v76, v77
	v_cvt_pk_bf16_f32 v77, v78, v79
	ds_write2_b64 v74, v[76:77], v[72:73] offset0:96 offset1:100
	v_add3_u32 v189, s12, v189, v212
	s_waitcnt vmcnt(0)
; __device__ __forceinline__ float row_rs(const float* ssq, int row) { return ssq ? rsqrtf(ssq[row] * (1.f / 1024.f) + RMS_EPS) : 1.f; }
; #define LAS __attribute__((address_space(3)))
; __device__ __forceinline__ unsigned pk2(float lo, float hi) { return pg8::cvt_pk_bf16(lo, hi); }
; __device__ __forceinline__ void stage_half(const bf16* g, LAS bf16* dst, int tid) {
;     v4u t[8];
; #pragma unroll
;     for (int i = 0; i < 8; ++i) { const int ch = tid + i * NT, r = ch >> 5, cc = ch & 31; t[i] = *(const v4u*)(g + (size_t)r * 1024 + cc * 8); }
; #pragma unroll
;     for (int i = 0; i < 8; ++i) { const int ch = tid + i * NT, r = ch >> 5, cc = ch & 31; *(LAS v4u*)(dst + r * XP + cc * 8) = t[i]; }
;     __device__ __forceinline__ void fused(f32x4 (&acc)[2][2][4][2], const pg8::Unit& u, int wr, int wc, int fr, int fq, LAS unsigned char* lds, int wid, int lane) const {
;         LAS bf16* QI = (LAS bf16*)lds;
; #pragma unroll
;         for (int ai = 0; ai < 2; ++ai)
; #pragma unroll
;             for (int m = 0; m < 4; ++m) { const int rl = ai * 128 + wr * 64 + m * 16 + fr; const float rs = pg8::row_rs(ssq, u.pm * 256 + rl);
; #pragma unroll
;                 for (int bj = 0; bj < 2; ++bj)
; #pragma unroll
;                     for (int n = 0; n < 2; ++n) { const f32x4 v = acc[ai][bj][m][n] * rs; v2u w; w.x = pk2(v[0], v[1]); w.y = pk2(v[2], v[3]);
;                         *(LAS v2u*)(QI + rl * XP + bj * 128 + wc * 32 + n * 16 + 4 * fq) = w; } }
	v_fmamk_f32 v64, v139, 0x3a800000, v129
	s_nop 0
	v_rsq_f32_e32 v64, v64
	s_nop 0
	v_mov_b32_e32 v66, v64
	v_pk_mul_f32 v[54:55], v[54:55], v[66:67] op_sel_hi:[1,0]
	v_pk_mul_f32 v[52:53], v[52:53], v[66:67] op_sel_hi:[1,0]
	v_pk_mul_f32 v[50:51], v[50:51], v[66:67] op_sel_hi:[1,0]
	v_pk_mul_f32 v[48:49], v[48:49], v[66:67] op_sel_hi:[1,0]
	v_cvt_pk_bf16_f32 v52, v52, v53
	v_cvt_pk_bf16_f32 v53, v54, v55
	v_cvt_pk_bf16_f32 v48, v48, v49
	v_cvt_pk_bf16_f32 v49, v50, v51
	v_add_u32_e32 v50, 0xe800, v113
	ds_write2_b64 v50, v[52:53], v[48:49] offset1:4
	v_pk_mul_f32 v[62:63], v[62:63], v[66:67] op_sel_hi:[1,0]
	v_pk_mul_f32 v[60:61], v[60:61], v[66:67] op_sel_hi:[1,0]
	v_pk_mul_f32 v[58:59], v[58:59], v[66:67] op_sel_hi:[1,0]
	v_pk_mul_f32 v[56:57], v[56:57], v[66:67] op_sel_hi:[1,0]
	v_cvt_pk_bf16_f32 v60, v60, v61
	v_cvt_pk_bf16_f32 v61, v62, v63
	v_cvt_pk_bf16_f32 v56, v56, v57
	v_cvt_pk_bf16_f32 v57, v58, v59
	v_add_u32_e32 v58, 0xe000, v113
	ds_write2_b64 v58, v[60:61], v[56:57] offset0:224 offset1:228
	v_add_u32_e32 v64, 0xe700, v113
	s_waitcnt vmcnt(0)
	v_fmamk_f32 v48, v140, 0x3a800000, v129
	s_nop 0
	v_rsq_f32_e32 v48, v48
	s_nop 0
	v_pk_mul_f32 v[38:39], v[38:39], v[48:49] op_sel_hi:[1,0]
	v_pk_mul_f32 v[36:37], v[36:37], v[48:49] op_sel_hi:[1,0]
	v_pk_mul_f32 v[34:35], v[34:35], v[48:49] op_sel_hi:[1,0]
	v_pk_mul_f32 v[32:33], v[32:33], v[48:49] op_sel_hi:[1,0]
	v_cvt_pk_bf16_f32 v36, v36, v37
	v_cvt_pk_bf16_f32 v37, v38, v39
	v_cvt_pk_bf16_f32 v32, v32, v33
	v_cvt_pk_bf16_f32 v33, v34, v35
	v_add_u32_e32 v34, 0xe800, v97
	ds_write2_b64 v34, v[36:37], v[32:33] offset1:4
	v_pk_mul_f32 v[46:47], v[46:47], v[48:49] op_sel_hi:[1,0]
	v_pk_mul_f32 v[44:45], v[44:45], v[48:49] op_sel_hi:[1,0]
	v_pk_mul_f32 v[42:43], v[42:43], v[48:49] op_sel_hi:[1,0]
	v_pk_mul_f32 v[40:41], v[40:41], v[48:49] op_sel_hi:[1,0]
	v_cvt_pk_bf16_f32 v44, v44, v45
	v_cvt_pk_bf16_f32 v45, v46, v47
	v_cvt_pk_bf16_f32 v40, v40, v41
	v_cvt_pk_bf16_f32 v41, v42, v43
	v_add_u32_e32 v42, 0xe000, v97
	ds_write2_b64 v42, v[44:45], v[40:41] offset0:224 offset1:228
	s_waitcnt vmcnt(0)
	v_fmamk_f32 v32, v141, 0x3a800000, v129
	s_nop 0
	v_rsq_f32_e32 v32, v32
	s_nop 0
	v_pk_mul_f32 v[22:23], v[22:23], v[32:33] op_sel_hi:[1,0]
	v_pk_mul_f32 v[20:21], v[20:21], v[32:33] op_sel_hi:[1,0]
	v_pk_mul_f32 v[18:19], v[18:19], v[32:33] op_sel_hi:[1,0]
	v_pk_mul_f32 v[16:17], v[16:17], v[32:33] op_sel_hi:[1,0]
	v_cvt_pk_bf16_f32 v20, v20, v21
	v_cvt_pk_bf16_f32 v21, v22, v23
	v_cvt_pk_bf16_f32 v16, v16, v17
	v_cvt_pk_bf16_f32 v17, v18, v19
	v_add_u32_e32 v18, 0xe800, v80
	ds_write2_b64 v18, v[20:21], v[16:17] offset1:4
	v_pk_mul_f32 v[30:31], v[30:31], v[32:33] op_sel_hi:[1,0]
	v_pk_mul_f32 v[28:29], v[28:29], v[32:33] op_sel_hi:[1,0]
	v_pk_mul_f32 v[26:27], v[26:27], v[32:33] op_sel_hi:[1,0]
	v_pk_mul_f32 v[24:25], v[24:25], v[32:33] op_sel_hi:[1,0]
	v_cvt_pk_bf16_f32 v28, v28, v29
	v_cvt_pk_bf16_f32 v29, v30, v31
	v_cvt_pk_bf16_f32 v24, v24, v25
	v_cvt_pk_bf16_f32 v25, v26, v27
	v_add_u32_e32 v26, 0xe000, v80
	v_or_b32_e32 v30, s30, v208
	ds_write2_b64 v26, v[28:29], v[24:25] offset0:224 offset1:228
	v_ashrrev_i32_e32 v34, 5, v30
	v_add_u32_e32 v20, 0xa00, v30
	v_add_u32_e32 v24, 0xc00, v30
	v_ashrrev_i32_e32 v44, 5, v20
	v_ashrrev_i32_e32 v46, 5, v24
	v_ashrrev_i32_e32 v35, 31, v34
	v_ashrrev_i32_e32 v45, 31, v44
	v_ashrrev_i32_e32 v47, 31, v46
	v_lshlrev_b64 v[192:193], 11, v[34:35]
	v_lshlrev_b64 v[202:203], 11, v[44:45]
	v_lshlrev_b64 v[204:205], 11, v[46:47]
	v_mul_lo_u32 v34, v34, s14
	v_add_u32_e32 v223, v216, v34
	v_add_u32_e32 v230, v215, v34
	s_waitcnt vmcnt(0)
	v_fmac_f32_e32 v129, 0x3a800000, v142
	s_lshl_b32 s6, s15, 8
	v_rsq_f32_e32 v16, v129
	s_ashr_i32 s7, s6, 31
	s_lshl_b64 s[4:5], s[6:7], 11
	s_add_u32 s10, s48, s4
	s_addc_u32 s19, s49, s5
	s_lshl_b32 s16, s34, 8
	v_pk_mul_f32 v[14:15], v[14:15], v[16:17] op_sel_hi:[1,0]
	v_pk_mul_f32 v[12:13], v[12:13], v[16:17] op_sel_hi:[1,0]
	v_pk_mul_f32 v[10:11], v[10:11], v[16:17] op_sel_hi:[1,0]
	v_pk_mul_f32 v[8:9], v[8:9], v[16:17] op_sel_hi:[1,0]
	v_pk_mul_f32 v[6:7], v[6:7], v[16:17] op_sel_hi:[1,0]
	v_pk_mul_f32 v[4:5], v[4:5], v[16:17] op_sel_hi:[1,0]
	v_pk_mul_f32 v[2:3], v[2:3], v[16:17] op_sel_hi:[1,0]
	v_pk_mul_f32 v[0:1], v[0:1], v[16:17] op_sel_hi:[1,0]
	s_ashr_i32 s17, s16, 31
	v_cvt_pk_bf16_f32 v12, v12, v13
	v_cvt_pk_bf16_f32 v13, v14, v15
	v_cvt_pk_bf16_f32 v8, v8, v9
	v_cvt_pk_bf16_f32 v9, v10, v11
	v_add_u32_e32 v10, 0x6000, v64
	v_cvt_pk_bf16_f32 v4, v4, v5
	v_cvt_pk_bf16_f32 v5, v6, v7
	v_cvt_pk_bf16_f32 v0, v0, v1
	v_cvt_pk_bf16_f32 v1, v2, v3
	s_lshl_b64 s[4:5], s[16:17], 1
	ds_write2_b64 v10, v[12:13], v[8:9] offset0:96 offset1:100
	ds_write2_b64 v10, v[4:5], v[0:1] offset0:128 offset1:132
	s_add_u32 s18, s10, s4
	v_add_u32_e32 v4, 0x200, v30
	v_add_u32_e32 v8, 0x400, v30
	v_add_u32_e32 v12, 0x600, v30
	v_add_u32_e32 v16, 0x800, v30
	v_add_u32_e32 v30, 0xe00, v30
	s_addc_u32 s19, s19, s5
	v_ashrrev_i32_e32 v36, 5, v4
	v_ashrrev_i32_e32 v38, 5, v8
	v_ashrrev_i32_e32 v40, 5, v12
	v_ashrrev_i32_e32 v42, 5, v16
	v_ashrrev_i32_e32 v48, 5, v30
	v_mul_lo_u32 v0, v214, s14
	v_lshl_add_u64 v[32:33], s[18:19], 0, v[190:191]
	s_mov_b64 s[18:19], 0x5600000
	v_ashrrev_i32_e32 v37, 31, v36
	v_ashrrev_i32_e32 v39, 31, v38
	v_ashrrev_i32_e32 v41, 31, v40
	v_ashrrev_i32_e32 v43, 31, v42
	v_ashrrev_i32_e32 v49, 31, v48
	v_add3_u32 v0, 0, v130, v0
	v_lshl_add_u64 v[28:29], v[32:33], 0, s[18:19]
	v_lshlrev_b64 v[194:195], 11, v[36:37]
	v_lshlrev_b64 v[196:197], 11, v[38:39]
	v_lshlrev_b64 v[198:199], 11, v[40:41]
	v_lshlrev_b64 v[200:201], 11, v[42:43]
	v_lshlrev_b64 v[206:207], 11, v[48:49]
	s_waitcnt lgkmcnt(0)
	s_barrier
; #define LAS __attribute__((address_space(3)))
; __device__ __forceinline__ void stage_half(const bf16* g, LAS bf16* dst, int tid) {
;     v4u t[8];
; #pragma unroll
;     for (int i = 0; i < 8; ++i) { const int ch = tid + i * NT, r = ch >> 5, cc = ch & 31; t[i] = *(const v4u*)(g + (size_t)r * 1024 + cc * 8); }
; #pragma unroll
;     for (int i = 0; i < 8; ++i) { const int ch = tid + i * NT, r = ch >> 5, cc = ch & 31; *(LAS v4u*)(dst + r * XP + cc * 8) = t[i]; }
; }
; __device__ __forceinline__ void xattn_core(unsigned char* ws, LAS unsigned char* lds, int b, int hd, int qb, int tid, const bf16x8 (&qf)[16]) {
;     const int lane = tid & 63, wave = tid >> 6, r32 = lane & 31, hh = lane >> 5;
;     LAS bf16* L0 = (LAS bf16*)lds; LAS bf16* L1 = L0 + 128 * XP;
;     const bf16* Kg = (const bf16*)(ws + WS_KB) + (size_t)(b * 256) * 1024 + hd * 256;
;     const bf16* Vg = (const bf16*)(ws + WS_VT) + (size_t)(hd * 256) * 1024 + b * 256;
;     stage_half(Kg, L0, tid); stage_half(Kg + (size_t)128 * 1024, L1, tid);
;     const int q0 = b * SEQ + qb * 256 + 32 * wave;
;     __syncthreads();
;     f32x16 sacc[8];
; #pragma unroll
;     for (int mt = 0; mt < 8; ++mt) {
; #pragma unroll
;         for (int r = 0; r < 16; ++r) sacc[mt][r] = 0.f;
;         const LAS bf16* kp = (mt < 4 ? L0 : L1) + ((mt & 3) * 32 + r32) * XP + 8 * hh;
; #pragma unroll
;         for (int ds = 0; ds < 16; ++ds) { const bf16x8 kf = *(const LAS bf16x8*)(kp + 16 * ds); sacc[mt] = __builtin_amdgcn_mfma_f32_32x32x16_bf16(kf, qf[ds], sacc[mt], 0, 0, 0); } }
;     __device__ __forceinline__ void fused(f32x4 (&acc)[2][2][4][2], const pg8::Unit& u, int wr, int wc, int fr, int fq, LAS unsigned char* lds, int wid, int lane) const {
;     ...
;         const int r32 = lane & 31, hh = lane >> 5; bf16x8 qf[16];
; #pragma unroll
;         for (int ds = 0; ds < 16; ++ds) qf[ds] = *(const LAS bf16x8*)(QI + (32 * wid + r32) * XP + 16 * ds + 8 * hh);
;         __syncthreads();
	ds_read_b128 v[112:115], v0
	ds_read_b128 v[184:187], v0 offset:32
	ds_read_b128 v[180:183], v0 offset:64
	ds_read_b128 v[176:179], v0 offset:96
	ds_read_b128 v[172:175], v0 offset:128
	ds_read_b128 v[168:171], v0 offset:160
	ds_read_b128 v[164:167], v0 offset:192
	ds_read_b128 v[160:163], v0 offset:224
	ds_read_b128 v[156:159], v0 offset:256
	ds_read_b128 v[152:155], v0 offset:288
	ds_read_b128 v[148:151], v0 offset:320
	ds_read_b128 v[144:147], v0 offset:352
	ds_read_b128 v[140:143], v0 offset:384
	ds_read_b128 v[136:139], v0 offset:416
	ds_read_b128 v[132:135], v0 offset:448
	ds_read_b128 v[128:131], v0 offset:480
	v_lshl_add_u64 v[0:1], v[28:29], 0, v[192:193]
	v_lshl_add_u64 v[4:5], v[28:29], 0, v[194:195]
	v_lshl_add_u64 v[8:9], v[28:29], 0, v[196:197]
	v_lshl_add_u64 v[12:13], v[28:29], 0, v[198:199]
	v_lshl_add_u64 v[16:17], v[28:29], 0, v[200:201]
	v_lshl_add_u64 v[20:21], v[28:29], 0, v[202:203]
	v_lshl_add_u64 v[24:25], v[28:29], 0, v[204:205]
	v_lshl_add_u64 v[28:29], v[28:29], 0, v[206:207]
	s_waitcnt lgkmcnt(0)
	s_barrier
	s_mov_b64 s[18:19], 0x5640000
	v_lshl_add_u64 v[100:101], v[32:33], 0, s[18:19]
	v_lshl_add_u64 v[72:73], v[100:101], 0, v[192:193]
	v_lshl_add_u64 v[76:77], v[100:101], 0, v[194:195]
	v_lshl_add_u64 v[80:81], v[100:101], 0, v[196:197]
	v_lshl_add_u64 v[84:85], v[100:101], 0, v[198:199]
	v_lshl_add_u64 v[88:89], v[100:101], 0, v[200:201]
	v_lshl_add_u64 v[92:93], v[100:101], 0, v[202:203]
	v_lshl_add_u64 v[96:97], v[100:101], 0, v[204:205]
	v_lshl_add_u64 v[100:101], v[100:101], 0, v[206:207]
	global_load_dwordx4 v[0:3], v[0:1], off
	v_mul_lo_u32 v35, v36, s14
	global_load_dwordx4 v[4:7], v[4:5], off
	v_mul_lo_u32 v36, v38, s14
	global_load_dwordx4 v[8:11], v[8:9], off
	v_mul_lo_u32 v37, v40, s14
	global_load_dwordx4 v[12:15], v[12:13], off
	v_mul_lo_u32 v38, v42, s14
	global_load_dwordx4 v[16:19], v[16:17], off
	v_mul_lo_u32 v39, v44, s14
	global_load_dwordx4 v[20:23], v[20:21], off
	v_mul_lo_u32 v40, v46, s14
	global_load_dwordx4 v[24:27], v[24:25], off
	v_mul_lo_u32 v41, v48, s14
	global_load_dwordx4 v[28:31], v[28:29], off
	global_load_dwordx4 v[72:75], v[72:73], off
	global_load_dwordx4 v[76:79], v[76:77], off
	global_load_dwordx4 v[80:83], v[80:81], off
	global_load_dwordx4 v[84:87], v[84:85], off
	global_load_dwordx4 v[88:91], v[88:89], off
	global_load_dwordx4 v[92:95], v[92:93], off
	global_load_dwordx4 v[96:99], v[96:97], off
	global_load_dwordx4 v[100:103], v[100:101], off
	v_add_u32_e32 v222, v216, v35
	v_add_u32_e32 v221, v216, v36
	v_add_u32_e32 v220, v216, v37
	v_add_u32_e32 v219, v216, v38
	v_add_u32_e32 v218, v216, v39
	v_add_u32_e32 v217, v216, v40
	v_add_u32_e32 v216, v216, v41
	s_mov_b64 s[18:19], 0x5640000
	v_add_u32_e32 v224, v215, v35
	v_add_u32_e32 v225, v215, v36
	v_add_u32_e32 v226, v215, v37
	v_add_u32_e32 v227, v215, v38
	v_add_u32_e32 v228, v215, v39
	v_add_u32_e32 v229, v215, v40
	v_add_u32_e32 v215, v215, v41
	s_lshl_b64 s[16:17], s[16:17], 11
	s_add_u32 s16, s48, s16
	s_addc_u32 s17, s49, s17
	s_and_b32 s10, s13, 0xf00
	s_lshl_b64 s[6:7], s[6:7], 1
	s_add_u32 s16, s16, s6
	s_addc_u32 s17, s17, s7
	s_lshl_b32 s6, s15, 12
	s_mov_b64 s[14:15], 0x5800000
	s_mov_b32 s7, 0xff61b1e6
	s_or_b32 s6, s10, s6
	s_waitcnt vmcnt(15)
	ds_write_b128 v223, v[0:3]
	s_waitcnt vmcnt(14)
	ds_write_b128 v222, v[4:7]
	s_waitcnt vmcnt(13)
	ds_write_b128 v221, v[8:11]
	s_waitcnt vmcnt(12)
	ds_write_b128 v220, v[12:15]
	s_waitcnt vmcnt(11)
	ds_write_b128 v219, v[16:19]
	s_waitcnt vmcnt(10)
	ds_write_b128 v218, v[20:23]
	s_waitcnt vmcnt(9)
	ds_write_b128 v217, v[24:27]
	s_waitcnt vmcnt(8)
	ds_write_b128 v216, v[28:31]
	s_waitcnt vmcnt(7)
	ds_write_b128 v230, v[72:75]
	s_waitcnt vmcnt(6)
	ds_write_b128 v224, v[76:79]
	s_waitcnt vmcnt(5)
	ds_write_b128 v225, v[80:83]
	s_waitcnt vmcnt(4)
	ds_write_b128 v226, v[84:87]
	s_waitcnt vmcnt(3)
	ds_write_b128 v227, v[88:91]
	s_waitcnt vmcnt(2)
	ds_write_b128 v228, v[92:95]
	s_waitcnt vmcnt(1)
	ds_write_b128 v229, v[96:99]
	s_waitcnt vmcnt(0)
	ds_write_b128 v215, v[100:103]
	s_waitcnt lgkmcnt(0)
	s_barrier
	ds_read_b128 v[236:239], v213
	ds_read_b128 v[240:243], v213 offset:32
	ds_read_b128 v[244:247], v213 offset:64
	s_waitcnt lgkmcnt(2)
	v_mfma_f32_32x32x16_bf16 v[96:111], v[236:239], v[112:115], 0
	ds_read_b128 v[236:239], v213 offset:96
	s_waitcnt lgkmcnt(2)
	v_mfma_f32_32x32x16_bf16 v[96:111], v[240:243], v[184:187], v[96:111]
	ds_read_b128 v[240:243], v213 offset:128
	s_waitcnt lgkmcnt(2)
	v_mfma_f32_32x32x16_bf16 v[96:111], v[244:247], v[180:183], v[96:111]
	ds_read_b128 v[244:247], v213 offset:160
	s_waitcnt lgkmcnt(2)
	v_mfma_f32_32x32x16_bf16 v[96:111], v[236:239], v[176:179], v[96:111]
	ds_read_b128 v[236:239], v213 offset:192
	s_waitcnt lgkmcnt(2)
	v_mfma_f32_32x32x16_bf16 v[96:111], v[240:243], v[172:175], v[96:111]
	ds_read_b128 v[240:243], v213 offset:224
	s_waitcnt lgkmcnt(2)
	v_mfma_f32_32x32x16_bf16 v[96:111], v[244:247], v[168:171], v[96:111]
	ds_read_b128 v[244:247], v213 offset:256
	s_waitcnt lgkmcnt(2)
	v_mfma_f32_32x32x16_bf16 v[96:111], v[236:239], v[164:167], v[96:111]
	ds_read_b128 v[236:239], v213 offset:288
	s_waitcnt lgkmcnt(2)
	v_mfma_f32_32x32x16_bf16 v[96:111], v[240:243], v[160:163], v[96:111]
	ds_read_b128 v[240:243], v213 offset:320
	s_waitcnt lgkmcnt(2)
	v_mfma_f32_32x32x16_bf16 v[96:111], v[244:247], v[156:159], v[96:111]
	ds_read_b128 v[244:247], v213 offset:352
	s_waitcnt lgkmcnt(2)
	v_mfma_f32_32x32x16_bf16 v[96:111], v[236:239], v[152:155], v[96:111]
	ds_read_b128 v[236:239], v213 offset:384
	s_waitcnt lgkmcnt(2)
	v_mfma_f32_32x32x16_bf16 v[96:111], v[240:243], v[148:151], v[96:111]
	ds_read_b128 v[240:243], v213 offset:416
	s_waitcnt lgkmcnt(2)
; #define LAS __attribute__((address_space(3)))
; __device__ __forceinline__ void xattn_core(unsigned char* ws, LAS unsigned char* lds, int b, int hd, int qb, int tid, const bf16x8 (&qf)[16]) {
;     ...
;     for (int mt = 0; mt < 8; ++mt) {
; #pragma unroll
;         for (int r = 0; r < 16; ++r) sacc[mt][r] = 0.f;
;         const LAS bf16* kp = (mt < 4 ? L0 : L1) + ((mt & 3) * 32 + r32) * XP + 8 * hh;
; #pragma unroll
;         for (int ds = 0; ds < 16; ++ds) { const bf16x8 kf = *(const LAS bf16x8*)(kp + 16 * ds); sacc[mt] = __builtin_amdgcn_mfma_f32_32x32x16_bf16(kf, qf[ds], sacc[mt], 0, 0, 0); } }
	v_mfma_f32_32x32x16_bf16 v[96:111], v[244:247], v[144:147], v[96:111]
	ds_read_b128 v[244:247], v213 offset:448
	s_waitcnt lgkmcnt(2)
	v_mfma_f32_32x32x16_bf16 v[96:111], v[236:239], v[140:143], v[96:111]
	ds_read_b128 v[236:239], v213 offset:480
	s_waitcnt lgkmcnt(2)
	v_mfma_f32_32x32x16_bf16 v[96:111], v[240:243], v[136:139], v[96:111]
	ds_read_b128 v[240:243], v213 offset:16896
	s_waitcnt lgkmcnt(2)
	v_mfma_f32_32x32x16_bf16 v[96:111], v[244:247], v[132:135], v[96:111]
	ds_read_b128 v[244:247], v213 offset:16928
	s_waitcnt lgkmcnt(2)
	v_mfma_f32_32x32x16_bf16 v[96:111], v[236:239], v[128:131], v[96:111]
	ds_read_b128 v[236:239], v213 offset:16960
	s_waitcnt lgkmcnt(2)
	v_mfma_f32_32x32x16_bf16 v[32:47], v[240:243], v[112:115], 0
	ds_read_b128 v[240:243], v213 offset:16992
	s_waitcnt lgkmcnt(2)
	v_mfma_f32_32x32x16_bf16 v[32:47], v[244:247], v[184:187], v[32:47]
	ds_read_b128 v[244:247], v213 offset:17024
	s_waitcnt lgkmcnt(2)
	v_mfma_f32_32x32x16_bf16 v[32:47], v[236:239], v[180:183], v[32:47]
	ds_read_b128 v[236:239], v213 offset:17056
	s_waitcnt lgkmcnt(2)
	v_mfma_f32_32x32x16_bf16 v[32:47], v[240:243], v[176:179], v[32:47]
	ds_read_b128 v[240:243], v213 offset:17088
	s_waitcnt lgkmcnt(2)
	v_mfma_f32_32x32x16_bf16 v[32:47], v[244:247], v[172:175], v[32:47]
	ds_read_b128 v[244:247], v213 offset:17120
	s_waitcnt lgkmcnt(2)
	v_mfma_f32_32x32x16_bf16 v[32:47], v[236:239], v[168:171], v[32:47]
	ds_read_b128 v[236:239], v213 offset:17152
	s_waitcnt lgkmcnt(2)
	v_mfma_f32_32x32x16_bf16 v[32:47], v[240:243], v[164:167], v[32:47]
	ds_read_b128 v[240:243], v213 offset:17184
	s_waitcnt lgkmcnt(2)
	v_mfma_f32_32x32x16_bf16 v[32:47], v[244:247], v[160:163], v[32:47]
	ds_read_b128 v[244:247], v213 offset:17216
	s_waitcnt lgkmcnt(2)
	v_mfma_f32_32x32x16_bf16 v[32:47], v[236:239], v[156:159], v[32:47]
	ds_read_b128 v[236:239], v213 offset:17248
	s_waitcnt lgkmcnt(2)
	v_mfma_f32_32x32x16_bf16 v[32:47], v[240:243], v[152:155], v[32:47]
	ds_read_b128 v[240:243], v213 offset:17280
	s_waitcnt lgkmcnt(2)
	v_mfma_f32_32x32x16_bf16 v[32:47], v[244:247], v[148:151], v[32:47]
	ds_read_b128 v[244:247], v213 offset:17312
	s_waitcnt lgkmcnt(2)
	v_mfma_f32_32x32x16_bf16 v[32:47], v[236:239], v[144:147], v[32:47]
	ds_read_b128 v[236:239], v213 offset:17344
	s_waitcnt lgkmcnt(2)
	v_mfma_f32_32x32x16_bf16 v[32:47], v[240:243], v[140:143], v[32:47]
	ds_read_b128 v[240:243], v213 offset:17376
	s_waitcnt lgkmcnt(2)
	v_mfma_f32_32x32x16_bf16 v[32:47], v[244:247], v[136:139], v[32:47]
	ds_read_b128 v[244:247], v213 offset:33792
	s_waitcnt lgkmcnt(2)
	v_mfma_f32_32x32x16_bf16 v[32:47], v[236:239], v[132:135], v[32:47]
	ds_read_b128 v[236:239], v213 offset:33824
	s_waitcnt lgkmcnt(2)
	v_mfma_f32_32x32x16_bf16 v[32:47], v[240:243], v[128:131], v[32:47]
	ds_read_b128 v[240:243], v213 offset:33856
	s_waitcnt lgkmcnt(2)
	v_mfma_f32_32x32x16_bf16 v[16:31], v[244:247], v[112:115], 0
	ds_read_b128 v[244:247], v213 offset:33888
	s_waitcnt lgkmcnt(2)
	v_mfma_f32_32x32x16_bf16 v[16:31], v[236:239], v[184:187], v[16:31]
	ds_read_b128 v[236:239], v213 offset:33920
	s_waitcnt lgkmcnt(2)
	v_mfma_f32_32x32x16_bf16 v[16:31], v[240:243], v[180:183], v[16:31]
	ds_read_b128 v[240:243], v213 offset:33952
	s_waitcnt lgkmcnt(2)
	v_mfma_f32_32x32x16_bf16 v[16:31], v[244:247], v[176:179], v[16:31]
	ds_read_b128 v[244:247], v213 offset:33984
	s_waitcnt lgkmcnt(2)
	v_mfma_f32_32x32x16_bf16 v[16:31], v[236:239], v[172:175], v[16:31]
	ds_read_b128 v[236:239], v213 offset:34016
	s_waitcnt lgkmcnt(2)
	v_mfma_f32_32x32x16_bf16 v[16:31], v[240:243], v[168:171], v[16:31]
	ds_read_b128 v[240:243], v213 offset:34048
	s_waitcnt lgkmcnt(2)
	v_mfma_f32_32x32x16_bf16 v[16:31], v[244:247], v[164:167], v[16:31]
	ds_read_b128 v[244:247], v213 offset:34080
	s_waitcnt lgkmcnt(2)
	v_mfma_f32_32x32x16_bf16 v[16:31], v[236:239], v[160:163], v[16:31]
	ds_read_b128 v[236:239], v213 offset:34112
	s_waitcnt lgkmcnt(2)
	v_mfma_f32_32x32x16_bf16 v[16:31], v[240:243], v[156:159], v[16:31]
	ds_read_b128 v[240:243], v213 offset:34144
	s_waitcnt lgkmcnt(2)
	v_mfma_f32_32x32x16_bf16 v[16:31], v[244:247], v[152:155], v[16:31]
	ds_read_b128 v[244:247], v213 offset:34176
	s_waitcnt lgkmcnt(2)
	v_mfma_f32_32x32x16_bf16 v[16:31], v[236:239], v[148:151], v[16:31]
	ds_read_b128 v[236:239], v213 offset:34208
	s_waitcnt lgkmcnt(2)
	v_mfma_f32_32x32x16_bf16 v[16:31], v[240:243], v[144:147], v[16:31]
	ds_read_b128 v[240:243], v213 offset:34240
	s_waitcnt lgkmcnt(2)
	v_mfma_f32_32x32x16_bf16 v[16:31], v[244:247], v[140:143], v[16:31]
	ds_read_b128 v[244:247], v213 offset:34272
	s_waitcnt lgkmcnt(2)
	v_mfma_f32_32x32x16_bf16 v[16:31], v[236:239], v[136:139], v[16:31]
	ds_read_b128 v[236:239], v213 offset:50688
	s_waitcnt lgkmcnt(2)
	v_mfma_f32_32x32x16_bf16 v[16:31], v[240:243], v[132:135], v[16:31]
	ds_read_b128 v[240:243], v213 offset:50720
	s_waitcnt lgkmcnt(2)
	v_mfma_f32_32x32x16_bf16 v[16:31], v[244:247], v[128:131], v[16:31]
	ds_read_b128 v[244:247], v213 offset:50752
	s_waitcnt lgkmcnt(2)
	v_mfma_f32_32x32x16_bf16 v[0:15], v[236:239], v[112:115], 0
	ds_read_b128 v[236:239], v213 offset:50784
	s_waitcnt lgkmcnt(2)
	v_mfma_f32_32x32x16_bf16 v[0:15], v[240:243], v[184:187], v[0:15]
	ds_read_b128 v[240:243], v213 offset:50816
	s_waitcnt lgkmcnt(2)
	v_mfma_f32_32x32x16_bf16 v[0:15], v[244:247], v[180:183], v[0:15]
	ds_read_b128 v[244:247], v213 offset:50848
	s_waitcnt lgkmcnt(2)
	v_mfma_f32_32x32x16_bf16 v[0:15], v[236:239], v[176:179], v[0:15]
	ds_read_b128 v[236:239], v213 offset:50880
	s_waitcnt lgkmcnt(2)
	v_mfma_f32_32x32x16_bf16 v[0:15], v[240:243], v[172:175], v[0:15]
	ds_read_b128 v[240:243], v213 offset:50912
	s_waitcnt lgkmcnt(2)
; #define LAS __attribute__((address_space(3)))
; __device__ __forceinline__ void xattn_core(unsigned char* ws, LAS unsigned char* lds, int b, int hd, int qb, int tid, const bf16x8 (&qf)[16]) {
;     ...
;     for (int mt = 0; mt < 8; ++mt) {
; #pragma unroll
;         for (int r = 0; r < 16; ++r) sacc[mt][r] = 0.f;
;         const LAS bf16* kp = (mt < 4 ? L0 : L1) + ((mt & 3) * 32 + r32) * XP + 8 * hh;
; #pragma unroll
;         for (int ds = 0; ds < 16; ++ds) { const bf16x8 kf = *(const LAS bf16x8*)(kp + 16 * ds); sacc[mt] = __builtin_amdgcn_mfma_f32_32x32x16_bf16(kf, qf[ds], sacc[mt], 0, 0, 0); } }
	v_mfma_f32_32x32x16_bf16 v[0:15], v[244:247], v[168:171], v[0:15]
	ds_read_b128 v[244:247], v213 offset:50944
	s_waitcnt lgkmcnt(2)
	v_mfma_f32_32x32x16_bf16 v[0:15], v[236:239], v[164:167], v[0:15]
	ds_read_b128 v[236:239], v213 offset:50976
	s_waitcnt lgkmcnt(2)
	v_mfma_f32_32x32x16_bf16 v[0:15], v[240:243], v[160:163], v[0:15]
	ds_read_b128 v[240:243], v213 offset:51008
	s_waitcnt lgkmcnt(2)
	v_mfma_f32_32x32x16_bf16 v[0:15], v[244:247], v[156:159], v[0:15]
	ds_read_b128 v[244:247], v213 offset:51040
	s_waitcnt lgkmcnt(2)
	v_mfma_f32_32x32x16_bf16 v[0:15], v[236:239], v[152:155], v[0:15]
	ds_read_b128 v[236:239], v213 offset:51072
	s_waitcnt lgkmcnt(2)
	v_mfma_f32_32x32x16_bf16 v[0:15], v[240:243], v[148:151], v[0:15]
	ds_read_b128 v[240:243], v213 offset:51104
	s_waitcnt lgkmcnt(2)
	v_mfma_f32_32x32x16_bf16 v[0:15], v[244:247], v[144:147], v[0:15]
	ds_read_b128 v[244:247], v213 offset:51136
	s_waitcnt lgkmcnt(2)
	v_mfma_f32_32x32x16_bf16 v[0:15], v[236:239], v[140:143], v[0:15]
	ds_read_b128 v[236:239], v213 offset:51168
	s_waitcnt lgkmcnt(2)
	v_mfma_f32_32x32x16_bf16 v[0:15], v[240:243], v[136:139], v[0:15]
	ds_read_b128 v[240:243], v68
	s_waitcnt lgkmcnt(2)
	v_mfma_f32_32x32x16_bf16 v[0:15], v[244:247], v[132:135], v[0:15]
	ds_read_b128 v[244:247], v68 offset:32
	s_waitcnt lgkmcnt(2)
	v_mfma_f32_32x32x16_bf16 v[0:15], v[236:239], v[128:131], v[0:15]
	ds_read_b128 v[236:239], v68 offset:64
	s_waitcnt lgkmcnt(2)
	v_mfma_f32_32x32x16_bf16 v[48:63], v[240:243], v[112:115], 0
	ds_read_b128 v[240:243], v68 offset:96
	s_waitcnt lgkmcnt(2)
	v_mfma_f32_32x32x16_bf16 v[48:63], v[244:247], v[184:187], v[48:63]
	ds_read_b128 v[244:247], v68 offset:128
	s_waitcnt lgkmcnt(2)
	v_mfma_f32_32x32x16_bf16 v[48:63], v[236:239], v[180:183], v[48:63]
	ds_read_b128 v[236:239], v68 offset:160
	s_waitcnt lgkmcnt(2)
	v_mfma_f32_32x32x16_bf16 v[48:63], v[240:243], v[176:179], v[48:63]
	ds_read_b128 v[240:243], v68 offset:192
	s_waitcnt lgkmcnt(2)
	v_mfma_f32_32x32x16_bf16 v[48:63], v[244:247], v[172:175], v[48:63]
	ds_read_b128 v[244:247], v68 offset:224
	s_waitcnt lgkmcnt(2)
	v_mfma_f32_32x32x16_bf16 v[48:63], v[236:239], v[168:171], v[48:63]
	ds_read_b128 v[236:239], v68 offset:256
	s_waitcnt lgkmcnt(2)
	v_mfma_f32_32x32x16_bf16 v[48:63], v[240:243], v[164:167], v[48:63]
	ds_read_b128 v[240:243], v68 offset:288
	s_waitcnt lgkmcnt(2)
	v_mfma_f32_32x32x16_bf16 v[48:63], v[244:247], v[160:163], v[48:63]
	ds_read_b128 v[244:247], v68 offset:320
	s_waitcnt lgkmcnt(2)
	v_mfma_f32_32x32x16_bf16 v[48:63], v[236:239], v[156:159], v[48:63]
	ds_read_b128 v[236:239], v68 offset:352
	s_waitcnt lgkmcnt(2)
	v_mfma_f32_32x32x16_bf16 v[48:63], v[240:243], v[152:155], v[48:63]
	ds_read_b128 v[240:243], v68 offset:384
	s_waitcnt lgkmcnt(2)
	v_mfma_f32_32x32x16_bf16 v[48:63], v[244:247], v[148:151], v[48:63]
	ds_read_b128 v[244:247], v68 offset:416
	s_waitcnt lgkmcnt(2)
	v_mfma_f32_32x32x16_bf16 v[48:63], v[236:239], v[144:147], v[48:63]
	ds_read_b128 v[236:239], v68 offset:448
	s_waitcnt lgkmcnt(2)
	v_mfma_f32_32x32x16_bf16 v[48:63], v[240:243], v[140:143], v[48:63]
	ds_read_b128 v[240:243], v68 offset:480
	s_waitcnt lgkmcnt(2)
	v_mfma_f32_32x32x16_bf16 v[48:63], v[244:247], v[136:139], v[48:63]
	ds_read_b128 v[244:247], v189 offset:16896
	s_waitcnt lgkmcnt(2)
	v_mfma_f32_32x32x16_bf16 v[48:63], v[236:239], v[132:135], v[48:63]
	ds_read_b128 v[236:239], v189 offset:16928
	s_waitcnt lgkmcnt(2)
	v_mfma_f32_32x32x16_bf16 v[48:63], v[240:243], v[128:131], v[48:63]
	ds_read_b128 v[240:243], v189 offset:16960
	s_waitcnt lgkmcnt(2)
	v_mfma_f32_32x32x16_bf16 v[80:95], v[244:247], v[112:115], 0
	ds_read_b128 v[244:247], v189 offset:16992
	s_waitcnt lgkmcnt(2)
	v_mfma_f32_32x32x16_bf16 v[80:95], v[236:239], v[184:187], v[80:95]
	ds_read_b128 v[236:239], v189 offset:17024
	s_waitcnt lgkmcnt(2)
	v_mfma_f32_32x32x16_bf16 v[80:95], v[240:243], v[180:183], v[80:95]
	ds_read_b128 v[240:243], v189 offset:17056
	s_waitcnt lgkmcnt(2)
	v_mfma_f32_32x32x16_bf16 v[80:95], v[244:247], v[176:179], v[80:95]
	ds_read_b128 v[244:247], v189 offset:17088
	s_waitcnt lgkmcnt(2)
	v_mfma_f32_32x32x16_bf16 v[80:95], v[236:239], v[172:175], v[80:95]
	ds_read_b128 v[236:239], v189 offset:17120
	s_waitcnt lgkmcnt(2)
	v_mfma_f32_32x32x16_bf16 v[80:95], v[240:243], v[168:171], v[80:95]
	ds_read_b128 v[240:243], v189 offset:17152
	s_waitcnt lgkmcnt(2)
	v_mfma_f32_32x32x16_bf16 v[80:95], v[244:247], v[164:167], v[80:95]
	ds_read_b128 v[244:247], v189 offset:17184
	s_waitcnt lgkmcnt(2)
	v_mfma_f32_32x32x16_bf16 v[80:95], v[236:239], v[160:163], v[80:95]
	ds_read_b128 v[236:239], v189 offset:17216
	s_waitcnt lgkmcnt(2)
	v_mfma_f32_32x32x16_bf16 v[80:95], v[240:243], v[156:159], v[80:95]
	ds_read_b128 v[240:243], v189 offset:17248
	s_waitcnt lgkmcnt(2)
	v_mfma_f32_32x32x16_bf16 v[80:95], v[244:247], v[152:155], v[80:95]
	ds_read_b128 v[244:247], v189 offset:17280
	s_waitcnt lgkmcnt(2)
	v_mfma_f32_32x32x16_bf16 v[80:95], v[236:239], v[148:151], v[80:95]
	ds_read_b128 v[236:239], v189 offset:17312
	s_waitcnt lgkmcnt(2)
	v_mfma_f32_32x32x16_bf16 v[80:95], v[240:243], v[144:147], v[80:95]
	ds_read_b128 v[240:243], v189 offset:17344
	s_waitcnt lgkmcnt(2)
	v_mfma_f32_32x32x16_bf16 v[80:95], v[244:247], v[140:143], v[80:95]
	ds_read_b128 v[244:247], v189 offset:17376
	s_waitcnt lgkmcnt(2)
	v_mfma_f32_32x32x16_bf16 v[80:95], v[236:239], v[136:139], v[80:95]
	ds_read_b128 v[236:239], v189 offset:33792
	s_waitcnt lgkmcnt(2)
	v_mfma_f32_32x32x16_bf16 v[80:95], v[240:243], v[132:135], v[80:95]
	ds_read_b128 v[240:243], v189 offset:33824
	s_waitcnt lgkmcnt(2)
	v_mfma_f32_32x32x16_bf16 v[80:95], v[244:247], v[128:131], v[80:95]
	ds_read_b128 v[244:247], v189 offset:33856
	s_waitcnt lgkmcnt(2)
; #define LAS __attribute__((address_space(3)))
; __device__ __forceinline__ void xattn_core(unsigned char* ws, LAS unsigned char* lds, int b, int hd, int qb, int tid, const bf16x8 (&qf)[16]) {
;     ...
;     for (int mt = 0; mt < 8; ++mt) {
; #pragma unroll
;         for (int r = 0; r < 16; ++r) sacc[mt][r] = 0.f;
;         const LAS bf16* kp = (mt < 4 ? L0 : L1) + ((mt & 3) * 32 + r32) * XP + 8 * hh;
; #pragma unroll
;         for (int ds = 0; ds < 16; ++ds) { const bf16x8 kf = *(const LAS bf16x8*)(kp + 16 * ds); sacc[mt] = __builtin_amdgcn_mfma_f32_32x32x16_bf16(kf, qf[ds], sacc[mt], 0, 0, 0); } }
;     __syncthreads();
;     stage_half(Vg, L0, tid); stage_half(Vg + (size_t)128 * 1024, L1, tid);
	v_mfma_f32_32x32x16_bf16 v[64:79], v[236:239], v[112:115], 0
	ds_read_b128 v[236:239], v189 offset:33888
	s_waitcnt lgkmcnt(2)
	v_mfma_f32_32x32x16_bf16 v[64:79], v[240:243], v[184:187], v[64:79]
	ds_read_b128 v[240:243], v189 offset:33920
	s_waitcnt lgkmcnt(2)
	v_mfma_f32_32x32x16_bf16 v[64:79], v[244:247], v[180:183], v[64:79]
	ds_read_b128 v[244:247], v189 offset:33952
	s_waitcnt lgkmcnt(2)
	v_mfma_f32_32x32x16_bf16 v[64:79], v[236:239], v[176:179], v[64:79]
	ds_read_b128 v[236:239], v189 offset:33984
	s_waitcnt lgkmcnt(2)
	v_mfma_f32_32x32x16_bf16 v[64:79], v[240:243], v[172:175], v[64:79]
	ds_read_b128 v[240:243], v189 offset:34016
	s_waitcnt lgkmcnt(2)
	v_mfma_f32_32x32x16_bf16 v[64:79], v[244:247], v[168:171], v[64:79]
	ds_read_b128 v[244:247], v189 offset:34048
	s_waitcnt lgkmcnt(2)
	v_mfma_f32_32x32x16_bf16 v[64:79], v[236:239], v[164:167], v[64:79]
	ds_read_b128 v[236:239], v189 offset:34080
	s_waitcnt lgkmcnt(2)
	v_mfma_f32_32x32x16_bf16 v[64:79], v[240:243], v[160:163], v[64:79]
	ds_read_b128 v[240:243], v189 offset:34112
	s_waitcnt lgkmcnt(2)
	v_mfma_f32_32x32x16_bf16 v[64:79], v[244:247], v[156:159], v[64:79]
	ds_read_b128 v[244:247], v189 offset:34144
	s_waitcnt lgkmcnt(2)
	v_mfma_f32_32x32x16_bf16 v[64:79], v[236:239], v[152:155], v[64:79]
	ds_read_b128 v[236:239], v189 offset:34176
	s_waitcnt lgkmcnt(2)
	v_mfma_f32_32x32x16_bf16 v[64:79], v[240:243], v[148:151], v[64:79]
	ds_read_b128 v[240:243], v189 offset:34208
	s_waitcnt lgkmcnt(2)
	v_mfma_f32_32x32x16_bf16 v[64:79], v[244:247], v[144:147], v[64:79]
	ds_read_b128 v[244:247], v189 offset:34240
	s_waitcnt lgkmcnt(2)
	v_mfma_f32_32x32x16_bf16 v[64:79], v[236:239], v[140:143], v[64:79]
	ds_read_b128 v[236:239], v189 offset:34272
	s_waitcnt lgkmcnt(2)
	v_mfma_f32_32x32x16_bf16 v[64:79], v[240:243], v[136:139], v[64:79]
	ds_read_b128 v[240:243], v189 offset:50688
	s_waitcnt lgkmcnt(2)
	v_mfma_f32_32x32x16_bf16 v[64:79], v[244:247], v[132:135], v[64:79]
	ds_read_b128 v[244:247], v189 offset:50720
	s_waitcnt lgkmcnt(2)
	v_mfma_f32_32x32x16_bf16 v[64:79], v[236:239], v[128:131], v[64:79]
	ds_read_b128 v[236:239], v189 offset:50752
	s_waitcnt lgkmcnt(2)
	v_mfma_f32_32x32x16_bf16 v[112:127], v[240:243], v[112:115], 0
	ds_read_b128 v[240:243], v189 offset:50784
	s_waitcnt lgkmcnt(2)
	v_mfma_f32_32x32x16_bf16 v[112:127], v[244:247], v[184:187], v[112:127]
	ds_read_b128 v[244:247], v189 offset:50816
	s_waitcnt lgkmcnt(2)
	v_mfma_f32_32x32x16_bf16 v[112:127], v[236:239], v[180:183], v[112:127]
	ds_read_b128 v[236:239], v189 offset:50848
	s_waitcnt lgkmcnt(2)
	v_mfma_f32_32x32x16_bf16 v[112:127], v[240:243], v[176:179], v[112:127]
	ds_read_b128 v[240:243], v189 offset:50880
	s_waitcnt lgkmcnt(2)
	v_mfma_f32_32x32x16_bf16 v[112:127], v[244:247], v[172:175], v[112:127]
	ds_read_b128 v[244:247], v189 offset:50912
	s_waitcnt lgkmcnt(2)
	v_mfma_f32_32x32x16_bf16 v[112:127], v[236:239], v[168:171], v[112:127]
	ds_read_b128 v[236:239], v189 offset:50944
	s_waitcnt lgkmcnt(2)
	v_mfma_f32_32x32x16_bf16 v[112:127], v[240:243], v[164:167], v[112:127]
	ds_read_b128 v[240:243], v189 offset:50976
	s_waitcnt lgkmcnt(2)
	v_mfma_f32_32x32x16_bf16 v[112:127], v[244:247], v[160:163], v[112:127]
	ds_read_b128 v[244:247], v189 offset:51008
	s_waitcnt lgkmcnt(2)
	v_mfma_f32_32x32x16_bf16 v[112:127], v[236:239], v[156:159], v[112:127]
	v_lshl_add_u64 v[160:161], s[16:17], 0, v[190:191]
	ds_read_b128 v[236:239], v189 offset:51040
	s_waitcnt lgkmcnt(2)
	v_mfma_f32_32x32x16_bf16 v[112:127], v[240:243], v[152:155], v[112:127]
	v_lshl_add_u64 v[156:157], v[160:161], 0, s[14:15]
	s_mov_b64 s[14:15], 0x5840000
	ds_read_b128 v[240:243], v189 offset:51072
	s_waitcnt lgkmcnt(2)
	v_mfma_f32_32x32x16_bf16 v[112:127], v[244:247], v[148:151], v[112:127]
	v_lshl_add_u64 v[152:153], v[156:157], 0, v[204:205]
	ds_read_b128 v[244:247], v189 offset:51104
	s_waitcnt lgkmcnt(2)
	v_mfma_f32_32x32x16_bf16 v[112:127], v[236:239], v[144:147], v[112:127]
	v_lshl_add_u64 v[148:149], v[156:157], 0, v[202:203]
	ds_read_b128 v[236:239], v189 offset:51136
	s_waitcnt lgkmcnt(2)
	v_mfma_f32_32x32x16_bf16 v[112:127], v[240:243], v[140:143], v[112:127]
	v_lshl_add_u64 v[144:145], v[156:157], 0, v[200:201]
	ds_read_b128 v[240:243], v189 offset:51168
	s_waitcnt lgkmcnt(2)
	v_mfma_f32_32x32x16_bf16 v[112:127], v[244:247], v[136:139], v[112:127]
	v_lshl_add_u64 v[140:141], v[156:157], 0, v[198:199]
	s_waitcnt lgkmcnt(1)
	v_mfma_f32_32x32x16_bf16 v[112:127], v[236:239], v[132:135], v[112:127]
	s_waitcnt lgkmcnt(0)
	s_barrier
; #define LAS __attribute__((address_space(3)))
; __device__ __forceinline__ void stage_half(const bf16* g, LAS bf16* dst, int tid) {
;     v4u t[8];
; #pragma unroll
;     for (int i = 0; i < 8; ++i) { const int ch = tid + i * NT, r = ch >> 5, cc = ch & 31; t[i] = *(const v4u*)(g + (size_t)r * 1024 + cc * 8); }
; #pragma unroll
;     for (int i = 0; i < 8; ++i) { const int ch = tid + i * NT, r = ch >> 5, cc = ch & 31; *(LAS v4u*)(dst + r * XP + cc * 8) = t[i]; }
; }
; __device__ __forceinline__ void xattn_core(unsigned char* ws, LAS unsigned char* lds, int b, int hd, int qb, int tid, const bf16x8 (&qf)[16]) {
;     ...
;     __syncthreads();
;     stage_half(Vg, L0, tid); stage_half(Vg + (size_t)128 * 1024, L1, tid);
;     float mx = -3.0e38f;
; #pragma unroll
;     for (int mt = 0; mt < 8; ++mt)
; #pragma unroll
;         for (int r = 0; r < 16; ++r) mx = fmaxf(mx, sacc[mt][r]);
;     mx = fmaxf(mx, __shfl_xor(mx, 32));
	v_lshl_add_u64 v[136:137], v[156:157], 0, v[196:197]
	global_load_dwordx4 v[136:139], v[136:137], off
	v_mov_b32_e32 v189, v191
	s_waitcnt lgkmcnt(0)
	v_mfma_f32_32x32x16_bf16 v[112:127], v[240:243], v[128:131], v[112:127]
	v_lshl_add_u64 v[128:129], v[156:157], 0, v[192:193]
	global_load_dwordx4 v[128:131], v[128:129], off
	v_lshl_add_u64 v[132:133], v[156:157], 0, v[194:195]
	global_load_dwordx4 v[132:135], v[132:133], off
	v_lshl_add_u64 v[156:157], v[156:157], 0, v[206:207]
	global_load_dwordx4 v[140:143], v[140:141], off
	s_nop 0
	global_load_dwordx4 v[144:147], v[144:145], off
	s_nop 0
	global_load_dwordx4 v[148:151], v[148:149], off
	s_nop 0
	global_load_dwordx4 v[152:155], v[152:153], off
	s_nop 0
	global_load_dwordx4 v[156:159], v[156:157], off
	s_waitcnt vmcnt(6)
	ds_write_b128 v223, v[128:131]
	s_waitcnt vmcnt(5)
	ds_write_b128 v222, v[132:135]
	ds_write_b128 v221, v[136:139]
	s_waitcnt vmcnt(4)
	ds_write_b128 v220, v[140:143]
	s_waitcnt vmcnt(3)
	ds_write_b128 v219, v[144:147]
	s_waitcnt vmcnt(2)
	ds_write_b128 v218, v[148:151]
	s_waitcnt vmcnt(1)
	ds_write_b128 v217, v[152:155]
	s_waitcnt vmcnt(0)
	ds_write_b128 v216, v[156:159]
	v_lshl_add_u64 v[156:157], v[160:161], 0, s[14:15]
	v_lshl_add_u64 v[128:129], v[156:157], 0, v[192:193]
	global_load_dwordx4 v[128:131], v[128:129], off
	v_lshl_add_u64 v[132:133], v[156:157], 0, v[194:195]
	global_load_dwordx4 v[132:135], v[132:133], off
	v_lshl_add_u64 v[136:137], v[156:157], 0, v[196:197]
	global_load_dwordx4 v[136:139], v[136:137], off
	v_lshl_add_u64 v[140:141], v[156:157], 0, v[198:199]
	global_load_dwordx4 v[140:143], v[140:141], off
	v_lshl_add_u64 v[144:145], v[156:157], 0, v[200:201]
	global_load_dwordx4 v[144:147], v[144:145], off
	v_lshl_add_u64 v[148:149], v[156:157], 0, v[202:203]
	global_load_dwordx4 v[148:151], v[148:149], off
	v_lshl_add_u64 v[152:153], v[156:157], 0, v[204:205]
	global_load_dwordx4 v[152:155], v[152:153], off
	v_lshl_add_u64 v[156:157], v[156:157], 0, v[206:207]
	global_load_dwordx4 v[156:159], v[156:157], off
	s_waitcnt vmcnt(7)
	ds_write_b128 v230, v[128:131]
	s_waitcnt vmcnt(6)
	ds_write_b128 v224, v[132:135]
	s_waitcnt vmcnt(5)
	ds_write_b128 v225, v[136:139]
	s_waitcnt vmcnt(4)
	ds_write_b128 v226, v[140:143]
	s_waitcnt vmcnt(3)
	ds_write_b128 v227, v[144:147]
	s_waitcnt vmcnt(2)
	ds_write_b128 v228, v[148:151]
	s_waitcnt vmcnt(1)
	ds_write_b128 v229, v[152:155]
	s_waitcnt vmcnt(0)
	ds_write_b128 v215, v[156:159]
	v_max3_f32 v128, v96, s7, v97
	v_max3_f32 v128, v128, v98, v99
	v_max3_f32 v128, v128, v100, v101
	v_max3_f32 v128, v128, v102, v103
	v_max3_f32 v128, v128, v104, v105
	v_max3_f32 v128, v128, v106, v107
	v_max3_f32 v128, v128, v108, v109
	v_max3_f32 v128, v128, v110, v111
	v_max3_f32 v128, v128, v32, v33
	v_max3_f32 v128, v128, v34, v35
	v_max3_f32 v128, v128, v36, v37
	v_max3_f32 v128, v128, v38, v39
	v_max3_f32 v128, v128, v40, v41
	v_max3_f32 v128, v128, v42, v43
	v_max3_f32 v128, v128, v44, v45
	v_max3_f32 v128, v128, v46, v47
	v_max3_f32 v128, v128, v16, v17
	v_max3_f32 v128, v128, v18, v19
	v_max3_f32 v128, v128, v20, v21
	v_max3_f32 v128, v128, v22, v23
	v_max3_f32 v128, v128, v24, v25
	v_max3_f32 v128, v128, v26, v27
	v_max3_f32 v128, v128, v28, v29
	v_max3_f32 v128, v128, v30, v31
	v_max3_f32 v128, v128, v0, v1
	v_max3_f32 v128, v128, v2, v3
	v_max3_f32 v128, v128, v4, v5
	v_max3_f32 v128, v128, v6, v7
	v_max3_f32 v128, v128, v8, v9
	v_max3_f32 v128, v128, v10, v11
	v_max3_f32 v128, v128, v12, v13
	v_max3_f32 v128, v128, v14, v15
	v_max3_f32 v128, v128, v48, v49
	v_max3_f32 v128, v128, v50, v51
	v_max3_f32 v128, v128, v52, v53
	v_max3_f32 v128, v128, v54, v55
	v_max3_f32 v128, v128, v56, v57
	v_max3_f32 v128, v128, v58, v59
	v_max3_f32 v128, v128, v60, v61
	v_max3_f32 v128, v128, v62, v63
	v_max3_f32 v128, v128, v80, v81
	v_max3_f32 v128, v128, v82, v83
	v_max3_f32 v128, v128, v84, v85
	v_max3_f32 v128, v128, v86, v87
	v_max3_f32 v128, v128, v88, v89
	v_max3_f32 v128, v128, v90, v91
	v_max3_f32 v128, v128, v92, v93
	v_max3_f32 v128, v128, v94, v95
	v_max3_f32 v128, v128, v64, v65
	v_max3_f32 v128, v128, v66, v67
	v_max3_f32 v128, v128, v68, v69
	v_max3_f32 v128, v128, v70, v71
	v_max3_f32 v128, v128, v72, v73
	v_max3_f32 v128, v128, v74, v75
	v_max3_f32 v128, v128, v76, v77
	v_max3_f32 v128, v128, v78, v79
	v_max3_f32 v128, v128, v112, v113
	v_max3_f32 v128, v128, v114, v115
	v_max3_f32 v128, v128, v116, v117
	v_max3_f32 v128, v128, v118, v119
	v_max3_f32 v128, v128, v120, v121
	v_max3_f32 v128, v128, v122, v123
	v_max3_f32 v128, v128, v124, v125
	v_max3_f32 v129, v128, v126, v127
	v_mbcnt_lo_u32_b32 v128, -1, 0
	v_mbcnt_hi_u32_b32 v128, -1, v128
	v_and_b32_e32 v131, 64, v128
	v_xor_b32_e32 v130, 32, v128
	v_add_u32_e32 v131, 64, v131
	v_cmp_lt_i32_e32 vcc, v130, v131
	s_waitcnt lgkmcnt(0)
	s_barrier
; __device__ __forceinline__ unsigned pk2(float lo, float hi) { return pg8::cvt_pk_bf16(lo, hi); }
; __device__ __forceinline__ void xattn_core(unsigned char* ws, LAS unsigned char* lds, int b, int hd, int qb, int tid, const bf16x8 (&qf)[16]) {
;     ...
;     mx = fmaxf(mx, __shfl_xor(mx, 32));
;     float sum = 0.f; bf16x8 pf[8][2];
; #pragma unroll
;     for (int mt = 0; mt < 8; ++mt) {
;         float e[16];
; #pragma unroll
;         for (int r = 0; r < 16; ++r) { e[r] = __expf(sacc[mt][r] - mx); sum += e[r]; }
; #pragma unroll
;         for (int s = 0; s < 2; ++s) { v4u w; w.x = pk2(e[8 * s], e[8 * s + 1]); w.y = pk2(e[8 * s + 2], e[8 * s + 3]); w.z = pk2(e[8 * s + 4], e[8 * s + 5]); w.w = pk2(e[8 * s + 6], e[8 * s + 7]); pf[mt][s] = __builtin_bit_cast(bf16x8, w); }
	v_cndmask_b32_e32 v128, v128, v130, vcc
	v_lshlrev_b32_e32 v128, 2, v128
	ds_bpermute_b32 v130, v128, v129
	s_waitcnt lgkmcnt(0)
	v_max_f32_e32 v130, v130, v130
	v_max_f32_e32 v129, v129, v130
	v_mov_b32_e32 v184, 0x3fb8aa3b
	v_mul_f32_e32 v185, 0xbfb8aa3b, v129
	v_fma_f32 v186, v96, v184, v185
	v_exp_f32_e32 v130, v186
	v_fma_f32 v187, v97, v184, v185
	v_exp_f32_e32 v131, v187
	v_fma_f32 v183, v98, v184, v185
	v_exp_f32_e32 v132, v183
	v_fma_f32 v182, v99, v184, v185
	v_exp_f32_e32 v133, v182
	v_fma_f32 v186, v100, v184, v185
	v_exp_f32_e32 v134, v186
	v_fma_f32 v187, v101, v184, v185
	v_exp_f32_e32 v135, v187
	v_fma_f32 v183, v102, v184, v185
	v_exp_f32_e32 v136, v183
	v_fma_f32 v182, v103, v184, v185
	v_exp_f32_e32 v137, v182
	v_fma_f32 v186, v104, v184, v185
	v_exp_f32_e32 v104, v186
	v_fma_f32 v187, v105, v184, v185
	v_exp_f32_e32 v105, v187
	v_fma_f32 v183, v106, v184, v185
	v_exp_f32_e32 v106, v183
	v_fma_f32 v182, v107, v184, v185
	v_exp_f32_e32 v107, v182
	v_fma_f32 v186, v108, v184, v185
	v_exp_f32_e32 v108, v186
	v_fma_f32 v187, v109, v184, v185
	v_exp_f32_e32 v109, v187
	v_fma_f32 v183, v110, v184, v185
	v_exp_f32_e32 v110, v183
	v_fma_f32 v182, v111, v184, v185
	v_exp_f32_e32 v111, v182
	v_cvt_pk_bf16_f32 v96, v130, v131
	v_add_f32_e32 v130, 0, v130
	v_add_f32_e32 v130, v131, v130
	v_add_f32_e32 v130, v132, v130
	v_add_f32_e32 v130, v133, v130
	v_add_f32_e32 v130, v134, v130
	v_add_f32_e32 v130, v135, v130
	v_add_f32_e32 v130, v136, v130
	v_add_f32_e32 v130, v137, v130
	v_fma_f32 v186, v32, v184, v185
	v_cvt_pk_bf16_f32 v100, v104, v105
	v_add_f32_e32 v104, v104, v130
	v_add_f32_e32 v104, v105, v104
	v_exp_f32_e32 v105, v186
	v_fma_f32 v187, v33, v184, v185
	v_cvt_pk_bf16_f32 v101, v106, v107
	v_add_f32_e32 v104, v106, v104
	v_exp_f32_e32 v106, v187
	v_fma_f32 v183, v34, v184, v185
	v_add_f32_e32 v104, v107, v104
	v_exp_f32_e32 v107, v183
	v_fma_f32 v182, v35, v184, v185
	v_cvt_pk_bf16_f32 v102, v108, v109
	v_add_f32_e32 v104, v108, v104
	v_exp_f32_e32 v108, v182
	v_fma_f32 v186, v36, v184, v185
	v_add_f32_e32 v104, v109, v104
	v_exp_f32_e32 v109, v186
	v_fma_f32 v187, v37, v184, v185
	v_cvt_pk_bf16_f32 v103, v110, v111
	v_add_f32_e32 v104, v110, v104
	v_exp_f32_e32 v110, v187
	v_fma_f32 v183, v38, v184, v185
	v_add_f32_e32 v104, v111, v104
	v_exp_f32_e32 v111, v183
	v_fma_f32 v182, v39, v184, v185
	v_exp_f32_e32 v130, v182
	v_fma_f32 v186, v40, v184, v185
	v_add_f32_e32 v104, v105, v104
	v_exp_f32_e32 v40, v186
	v_fma_f32 v187, v41, v184, v185
	v_add_f32_e32 v104, v106, v104
	v_add_f32_e32 v104, v107, v104
	v_exp_f32_e32 v41, v187
	v_fma_f32 v183, v42, v184, v185
	v_add_f32_e32 v104, v108, v104
	v_add_f32_e32 v104, v109, v104
	v_exp_f32_e32 v42, v183
	v_fma_f32 v182, v43, v184, v185
	v_add_f32_e32 v104, v110, v104
	v_add_f32_e32 v104, v111, v104
	v_exp_f32_e32 v43, v182
	v_fma_f32 v186, v44, v184, v185
	v_add_f32_e32 v104, v130, v104
	v_fma_f32 v187, v16, v184, v185
	v_cvt_pk_bf16_f32 v36, v40, v41
	v_add_f32_e32 v40, v40, v104
	v_exp_f32_e32 v44, v186
	v_fma_f32 v183, v45, v184, v185
	v_add_f32_e32 v40, v41, v40
	v_exp_f32_e32 v41, v187
	v_fma_f32 v182, v17, v184, v185
	v_exp_f32_e32 v45, v183
	v_fma_f32 v186, v46, v184, v185
	v_cvt_pk_bf16_f32 v37, v42, v43
	v_add_f32_e32 v40, v42, v40
	v_exp_f32_e32 v42, v182
	v_fma_f32 v187, v18, v184, v185
	v_exp_f32_e32 v46, v186
	v_fma_f32 v183, v47, v184, v185
	v_add_f32_e32 v40, v43, v40
	v_exp_f32_e32 v43, v187
	v_fma_f32 v182, v19, v184, v185
	v_exp_f32_e32 v47, v183
	v_cvt_pk_bf16_f32 v38, v44, v45
	v_add_f32_e32 v40, v44, v40
	v_exp_f32_e32 v44, v182
	v_fma_f32 v186, v20, v184, v185
	v_add_f32_e32 v40, v45, v40
	v_exp_f32_e32 v45, v186
	v_fma_f32 v187, v21, v184, v185
	v_cvt_pk_bf16_f32 v39, v46, v47
	v_add_f32_e32 v40, v46, v40
	v_exp_f32_e32 v46, v187
	v_fma_f32 v183, v22, v184, v185
	v_add_f32_e32 v40, v47, v40
	v_exp_f32_e32 v47, v183
	v_fma_f32 v182, v23, v184, v185
	v_exp_f32_e32 v104, v182
	v_fma_f32 v186, v24, v184, v185
	v_exp_f32_e32 v24, v186
	v_fma_f32 v187, v25, v184, v185
	v_exp_f32_e32 v25, v187
	v_fma_f32 v183, v26, v184, v185
	v_add_f32_e32 v40, v41, v40
	v_exp_f32_e32 v26, v183
	v_fma_f32 v182, v27, v184, v185
	v_add_f32_e32 v40, v42, v40
	v_add_f32_e32 v40, v43, v40
	v_exp_f32_e32 v27, v182
	v_fma_f32 v186, v28, v184, v185
	v_add_f32_e32 v40, v44, v40
	v_add_f32_e32 v40, v45, v40
	v_exp_f32_e32 v28, v186
	v_fma_f32 v187, v29, v184, v185
	v_add_f32_e32 v40, v46, v40
	v_add_f32_e32 v40, v47, v40
	v_exp_f32_e32 v29, v187
	v_fma_f32 v183, v30, v184, v185
	v_add_f32_e32 v40, v104, v40
	v_cvt_pk_bf16_f32 v20, v24, v25
	v_add_f32_e32 v24, v24, v40
	v_exp_f32_e32 v30, v183
	v_fma_f32 v182, v31, v184, v185
	v_add_f32_e32 v24, v25, v24
	v_add_f32_e32 v24, v26, v24
	v_fma_f32 v0, v0, v184, v185
	v_fma_f32 v1, v1, v184, v185
	v_exp_f32_e32 v31, v182
	v_add_f32_e32 v24, v27, v24
	v_add_f32_e32 v24, v28, v24
	v_exp_f32_e32 v0, v0
	v_exp_f32_e32 v1, v1
	v_fma_f32 v2, v2, v184, v185
	v_add_f32_e32 v24, v29, v24
	v_fma_f32 v3, v3, v184, v185
	v_add_f32_e32 v24, v30, v24
	v_exp_f32_e32 v2, v2
	v_fma_f32 v4, v4, v184, v185
	v_add_f32_e32 v40, v31, v24
	v_exp_f32_e32 v3, v3
	v_fma_f32 v5, v5, v184, v185
	v_exp_f32_e32 v4, v4
	v_fma_f32 v6, v6, v184, v185
	v_cvt_pk_bf16_f32 v24, v0, v1
	v_add_f32_e32 v0, v0, v40
	v_exp_f32_e32 v5, v5
	v_fma_f32 v7, v7, v184, v185
	v_add_f32_e32 v0, v1, v0
	v_exp_f32_e32 v6, v6
	v_fma_f32 v8, v8, v184, v185
	v_add_f32_e32 v0, v2, v0
	v_exp_f32_e32 v7, v7
	v_fma_f32 v9, v9, v184, v185
	v_add_f32_e32 v0, v3, v0
	v_exp_f32_e32 v8, v8
	v_fma_f32 v10, v10, v184, v185
	v_add_f32_e32 v0, v4, v0
	v_exp_f32_e32 v9, v9
	v_fma_f32 v11, v11, v184, v185
; __device__ __forceinline__ unsigned pk2(float lo, float hi) { return pg8::cvt_pk_bf16(lo, hi); }
; __device__ __forceinline__ void xattn_core(unsigned char* ws, LAS unsigned char* lds, int b, int hd, int qb, int tid, const bf16x8 (&qf)[16]) {
;     ...
;     float sum = 0.f; bf16x8 pf[8][2];
; #pragma unroll
;     for (int mt = 0; mt < 8; ++mt) {
;         float e[16];
; #pragma unroll
;         for (int r = 0; r < 16; ++r) { e[r] = __expf(sacc[mt][r] - mx); sum += e[r]; }
; #pragma unroll
;         for (int s = 0; s < 2; ++s) { v4u w; w.x = pk2(e[8 * s], e[8 * s + 1]); w.y = pk2(e[8 * s + 2], e[8 * s + 3]); w.z = pk2(e[8 * s + 4], e[8 * s + 5]); w.w = pk2(e[8 * s + 6], e[8 * s + 7]); pf[mt][s] = __builtin_bit_cast(bf16x8, w); }
;     }
;     sum += __shfl_xor(sum, 32);
;     const float inv = 1.f / sum;
	v_add_f32_e32 v0, v5, v0
	v_exp_f32_e32 v10, v10
	v_fma_f32 v12, v12, v184, v185
	v_add_f32_e32 v0, v6, v0
	v_exp_f32_e32 v11, v11
	v_fma_f32 v13, v13, v184, v185
	v_add_f32_e32 v0, v7, v0
	v_exp_f32_e32 v12, v12
	v_fma_f32 v14, v14, v184, v185
	v_add_f32_e32 v0, v8, v0
	v_exp_f32_e32 v13, v13
	v_fma_f32 v15, v15, v184, v185
	v_add_f32_e32 v0, v9, v0
	v_exp_f32_e32 v14, v14
	v_add_f32_e32 v0, v10, v0
	v_fma_f32 v1, v48, v184, v185
	v_exp_f32_e32 v15, v15
	v_cvt_pk_bf16_f32 v25, v2, v3
	v_add_f32_e32 v0, v11, v0
	v_fma_f32 v2, v49, v184, v185
	v_add_f32_e32 v0, v12, v0
	v_exp_f32_e32 v1, v1
	v_fma_f32 v3, v50, v184, v185
	v_cvt_pk_bf16_f32 v21, v26, v27
	v_cvt_pk_bf16_f32 v26, v4, v5
	v_add_f32_e32 v0, v13, v0
	v_exp_f32_e32 v2, v2
	v_fma_f32 v4, v51, v184, v185
	v_add_f32_e32 v0, v14, v0
	v_exp_f32_e32 v3, v3
	v_fma_f32 v5, v52, v184, v185
	v_cvt_pk_bf16_f32 v27, v6, v7
	v_add_f32_e32 v0, v15, v0
	v_exp_f32_e32 v4, v4
	v_fma_f32 v6, v53, v184, v185
	v_exp_f32_e32 v5, v5
	v_fma_f32 v7, v54, v184, v185
	v_add_f32_e32 v0, v1, v0
	v_cvt_pk_bf16_f32 v22, v28, v29
	v_cvt_pk_bf16_f32 v28, v8, v9
	v_exp_f32_e32 v6, v6
	v_fma_f32 v8, v55, v184, v185
	v_add_f32_e32 v0, v2, v0
	v_exp_f32_e32 v7, v7
	v_fma_f32 v9, v56, v184, v185
	v_add_f32_e32 v0, v3, v0
	v_cvt_pk_bf16_f32 v29, v10, v11
	v_exp_f32_e32 v8, v8
	v_fma_f32 v10, v57, v184, v185
	v_add_f32_e32 v0, v4, v0
	v_exp_f32_e32 v9, v9
	v_fma_f32 v11, v58, v184, v185
	v_add_f32_e32 v0, v5, v0
	v_cvt_pk_bf16_f32 v23, v30, v31
	v_cvt_pk_bf16_f32 v30, v12, v13
	v_exp_f32_e32 v10, v10
	v_fma_f32 v12, v59, v184, v185
	v_add_f32_e32 v0, v6, v0
	v_exp_f32_e32 v11, v11
	v_fma_f32 v13, v60, v184, v185
	v_add_f32_e32 v0, v7, v0
	v_cvt_pk_bf16_f32 v31, v14, v15
	v_exp_f32_e32 v12, v12
	v_fma_f32 v14, v61, v184, v185
	v_add_f32_e32 v0, v8, v0
	v_exp_f32_e32 v13, v13
	v_fma_f32 v15, v62, v184, v185
	v_fma_f32 v186, v63, v184, v185
	v_add_f32_e32 v0, v9, v0
	v_exp_f32_e32 v14, v14
	v_add_f32_e32 v0, v10, v0
	v_exp_f32_e32 v15, v15
	v_exp_f32_e32 v48, v186
	v_cvt_pk_bf16_f32 v40, v1, v2
	v_add_f32_e32 v0, v11, v0
	v_fma_f32 v1, v80, v184, v185
	v_add_f32_e32 v0, v12, v0
	v_fma_f32 v2, v81, v184, v185
	v_cvt_pk_bf16_f32 v16, v41, v42
	v_cvt_pk_bf16_f32 v41, v3, v4
	v_add_f32_e32 v0, v13, v0
	v_exp_f32_e32 v1, v1
	v_fma_f32 v3, v82, v184, v185
	v_add_f32_e32 v0, v14, v0
	v_exp_f32_e32 v2, v2
	v_fma_f32 v4, v83, v184, v185
	v_cvt_pk_bf16_f32 v42, v5, v6
	v_add_f32_e32 v0, v15, v0
	v_exp_f32_e32 v3, v3
	v_fma_f32 v5, v84, v184, v185
	v_add_f32_e32 v0, v48, v0
	v_exp_f32_e32 v4, v4
	v_fma_f32 v6, v85, v184, v185
	v_cvt_pk_bf16_f32 v17, v43, v44
	v_cvt_pk_bf16_f32 v43, v7, v8
	v_exp_f32_e32 v5, v5
	v_fma_f32 v7, v86, v184, v185
	v_add_f32_e32 v0, v1, v0
	v_exp_f32_e32 v6, v6
	v_fma_f32 v8, v87, v184, v185
	v_add_f32_e32 v0, v2, v0
	v_cvt_pk_bf16_f32 v44, v9, v10
	v_exp_f32_e32 v7, v7
	v_fma_f32 v9, v88, v184, v185
	v_add_f32_e32 v0, v3, v0
	v_exp_f32_e32 v8, v8
	v_fma_f32 v10, v89, v184, v185
	v_add_f32_e32 v0, v4, v0
	v_cvt_pk_bf16_f32 v18, v45, v46
	v_cvt_pk_bf16_f32 v45, v11, v12
	v_exp_f32_e32 v9, v9
	v_fma_f32 v11, v90, v184, v185
	v_add_f32_e32 v0, v5, v0
	v_exp_f32_e32 v10, v10
	v_fma_f32 v12, v91, v184, v185
	v_add_f32_e32 v0, v6, v0
	v_cvt_pk_bf16_f32 v46, v13, v14
	v_exp_f32_e32 v11, v11
	v_fma_f32 v13, v92, v184, v185
	v_add_f32_e32 v0, v7, v0
	v_exp_f32_e32 v12, v12
	v_fma_f32 v14, v93, v184, v185
	v_add_f32_e32 v0, v8, v0
	v_cvt_pk_bf16_f32 v19, v47, v104
	v_cvt_pk_bf16_f32 v47, v15, v48
	v_exp_f32_e32 v13, v13
	v_fma_f32 v15, v94, v184, v185
	v_fma_f32 v187, v95, v184, v185
	v_add_f32_e32 v0, v9, v0
	v_exp_f32_e32 v14, v14
	v_add_f32_e32 v0, v10, v0
	v_exp_f32_e32 v15, v15
	v_exp_f32_e32 v56, v187
	v_cvt_pk_bf16_f32 v48, v1, v2
	v_add_f32_e32 v0, v11, v0
	v_fma_f32 v1, v64, v184, v185
	v_add_f32_e32 v0, v12, v0
	v_fma_f32 v2, v65, v184, v185
	v_cvt_pk_bf16_f32 v49, v3, v4
	v_add_f32_e32 v0, v13, v0
	v_exp_f32_e32 v1, v1
	v_fma_f32 v3, v66, v184, v185
	v_add_f32_e32 v0, v14, v0
	v_exp_f32_e32 v2, v2
	v_fma_f32 v4, v67, v184, v185
	v_cvt_pk_bf16_f32 v50, v5, v6
	v_add_f32_e32 v0, v15, v0
	v_exp_f32_e32 v3, v3
; __device__ __forceinline__ unsigned pk2(float lo, float hi) { return pg8::cvt_pk_bf16(lo, hi); }
; __device__ __forceinline__ void xattn_core(unsigned char* ws, LAS unsigned char* lds, int b, int hd, int qb, int tid, const bf16x8 (&qf)[16]) {
;     ...
;     float sum = 0.f; bf16x8 pf[8][2];
; #pragma unroll
;     for (int mt = 0; mt < 8; ++mt) {
;         float e[16];
; #pragma unroll
;         for (int r = 0; r < 16; ++r) { e[r] = __expf(sacc[mt][r] - mx); sum += e[r]; }
; #pragma unroll
;         for (int s = 0; s < 2; ++s) { v4u w; w.x = pk2(e[8 * s], e[8 * s + 1]); w.y = pk2(e[8 * s + 2], e[8 * s + 3]); w.z = pk2(e[8 * s + 4], e[8 * s + 5]); w.w = pk2(e[8 * s + 6], e[8 * s + 7]); pf[mt][s] = __builtin_bit_cast(bf16x8, w); }
;     }
;     sum += __shfl_xor(sum, 32);
;     const float inv = 1.f / sum;
;     __syncthreads();
;     bf16* op = (bf16*)(ws + WS_O) + (size_t)(q0 + r32) * 1024 + hd * 256 + 4 * hh;
	v_fma_f32 v5, v68, v184, v185
	v_add_f32_e32 v0, v56, v0
	v_exp_f32_e32 v4, v4
	v_fma_f32 v6, v69, v184, v185
	v_cvt_pk_bf16_f32 v51, v7, v8
	v_exp_f32_e32 v5, v5
	v_fma_f32 v7, v70, v184, v185
	v_add_f32_e32 v0, v1, v0
	v_exp_f32_e32 v6, v6
	v_fma_f32 v8, v71, v184, v185
	v_add_f32_e32 v0, v2, v0
	v_cvt_pk_bf16_f32 v52, v9, v10
	v_exp_f32_e32 v7, v7
	v_fma_f32 v9, v72, v184, v185
	v_add_f32_e32 v0, v3, v0
	v_exp_f32_e32 v8, v8
	v_fma_f32 v10, v73, v184, v185
	v_add_f32_e32 v0, v4, v0
	v_cvt_pk_bf16_f32 v53, v11, v12
	v_exp_f32_e32 v9, v9
	v_fma_f32 v11, v74, v184, v185
	v_add_f32_e32 v0, v5, v0
	v_exp_f32_e32 v10, v10
	v_fma_f32 v12, v75, v184, v185
	v_add_f32_e32 v0, v6, v0
	v_cvt_pk_bf16_f32 v54, v13, v14
	v_exp_f32_e32 v11, v11
	v_fma_f32 v13, v76, v184, v185
	v_add_f32_e32 v0, v7, v0
	v_exp_f32_e32 v12, v12
	v_fma_f32 v14, v77, v184, v185
	v_add_f32_e32 v0, v8, v0
	v_cvt_pk_bf16_f32 v55, v15, v56
	v_exp_f32_e32 v13, v13
	v_fma_f32 v15, v78, v184, v185
	v_fma_f32 v183, v79, v184, v185
	v_add_f32_e32 v0, v9, v0
	v_exp_f32_e32 v14, v14
	v_add_f32_e32 v0, v10, v0
	v_exp_f32_e32 v15, v15
	v_exp_f32_e32 v64, v183
	v_cvt_pk_bf16_f32 v56, v1, v2
	v_add_f32_e32 v0, v11, v0
	v_fma_f32 v1, v112, v184, v185
	v_add_f32_e32 v0, v12, v0
	v_fma_f32 v2, v113, v184, v185
	v_cvt_pk_bf16_f32 v57, v3, v4
	v_add_f32_e32 v0, v13, v0
	v_exp_f32_e32 v1, v1
	v_fma_f32 v3, v114, v184, v185
	v_add_f32_e32 v0, v14, v0
	v_exp_f32_e32 v2, v2
	v_fma_f32 v4, v115, v184, v185
	v_cvt_pk_bf16_f32 v58, v5, v6
	v_add_f32_e32 v0, v15, v0
	v_exp_f32_e32 v3, v3
	v_fma_f32 v5, v116, v184, v185
	v_add_f32_e32 v0, v64, v0
	v_exp_f32_e32 v4, v4
	v_fma_f32 v6, v117, v184, v185
	v_cvt_pk_bf16_f32 v59, v7, v8
	v_exp_f32_e32 v5, v5
	v_fma_f32 v7, v118, v184, v185
	v_add_f32_e32 v0, v1, v0
	v_exp_f32_e32 v6, v6
	v_fma_f32 v8, v119, v184, v185
	v_add_f32_e32 v0, v2, v0
	v_cvt_pk_bf16_f32 v60, v9, v10
	v_exp_f32_e32 v7, v7
	v_fma_f32 v9, v120, v184, v185
	v_add_f32_e32 v0, v3, v0
	v_exp_f32_e32 v8, v8
	v_fma_f32 v10, v121, v184, v185
	v_add_f32_e32 v0, v4, v0
	v_cvt_pk_bf16_f32 v61, v11, v12
	v_exp_f32_e32 v9, v9
	v_fma_f32 v11, v122, v184, v185
	v_add_f32_e32 v0, v5, v0
	v_exp_f32_e32 v10, v10
	v_fma_f32 v12, v123, v184, v185
	v_add_f32_e32 v0, v6, v0
	v_cvt_pk_bf16_f32 v62, v13, v14
	v_exp_f32_e32 v11, v11
	v_fma_f32 v13, v124, v184, v185
	v_add_f32_e32 v0, v7, v0
	v_exp_f32_e32 v12, v12
	v_fma_f32 v14, v125, v184, v185
	v_add_f32_e32 v0, v8, v0
	v_cvt_pk_bf16_f32 v63, v15, v64
	v_exp_f32_e32 v13, v13
	v_fma_f32 v15, v126, v184, v185
	v_add_f32_e32 v0, v9, v0
	v_exp_f32_e32 v14, v14
	v_fma_f32 v182, v127, v184, v185
	v_add_f32_e32 v0, v10, v0
	v_exp_f32_e32 v15, v15
	v_add_f32_e32 v0, v11, v0
	v_exp_f32_e32 v72, v182
	v_add_f32_e32 v0, v12, v0
	v_add_f32_e32 v0, v13, v0
	v_add_f32_e32 v0, v14, v0
	v_add_f32_e32 v0, v15, v0
	v_add_f32_e32 v0, v72, v0
	v_cvt_pk_bf16_f32 v64, v1, v2
	ds_bpermute_b32 v1, v128, v0
	v_cvt_pk_bf16_f32 v65, v3, v4
	v_cvt_pk_bf16_f32 v66, v5, v6
	v_cvt_pk_bf16_f32 v71, v15, v72
	v_cvt_pk_bf16_f32 v97, v132, v133
	s_waitcnt lgkmcnt(0)
	v_add_f32_e32 v0, v0, v1
	v_div_scale_f32 v1, s[14:15], v0, v0, 1.0
	v_rcp_f32_e32 v2, v1
	v_cvt_pk_bf16_f32 v98, v134, v135
	v_cvt_pk_bf16_f32 v99, v136, v137
	v_cvt_pk_bf16_f32 v32, v105, v106
	v_fma_f32 v3, -v1, v2, 1.0
	v_fmac_f32_e32 v2, v3, v2
	v_div_scale_f32 v3, vcc, 1.0, v0, 1.0
	v_mul_f32_e32 v4, v3, v2
	v_fma_f32 v5, -v1, v4, v3
	v_fmac_f32_e32 v4, v5, v2
	v_fma_f32 v1, -v1, v4, v3
	v_div_fmas_f32 v1, v1, v2, v4
	v_div_fixup_f32 v72, v1, v0, 1.0
	v_add_u32_e32 v0, s6, v214
	v_ashrrev_i32_e32 v1, 31, v0
	v_lshlrev_b64 v[0:1], 11, v[0:1]
	v_lshl_add_u64 v[2:3], s[48:49], 0, v[188:189]
	v_lshl_add_u64 v[0:1], v[0:1], 0, s[4:5]
	v_lshl_add_u64 v[0:1], v[2:3], 0, v[0:1]
	s_mov_b64 s[4:5], 0xc000020
	v_cvt_pk_bf16_f32 v33, v107, v108
	v_cvt_pk_bf16_f32 v34, v109, v110
	v_cvt_pk_bf16_f32 v35, v111, v130
	v_cvt_pk_bf16_f32 v67, v7, v8
	v_cvt_pk_bf16_f32 v68, v9, v10
	v_cvt_pk_bf16_f32 v69, v11, v12
	v_cvt_pk_bf16_f32 v70, v13, v14
	v_mov_b32_e32 v73, v72
	v_lshl_add_u64 v[74:75], v[0:1], 0, s[4:5]
	v_lshlrev_b32_e32 v76, 1, v211
	s_mov_b32 s4, 0
